# gMLP item epilogue: gate-input and bias loads of 15 rows issued together (was one exposed round trip per row)
# baseline (speedup 1.0000x reference)
.LBB0_309:
	s_or_b64 exec, exec, s[0:1]
	v_and_b32_e32 v6, 0x7f, v12
	v_or_b32_e32 v0, s4, v6
	v_readlane_b32 s2, v251, 25
	v_lshlrev_b32_e32 v0, 9, v0
	v_readlane_b32 s3, v251, 26
	s_and_b32 s0, s40, 3
	s_lshl_b32 s56, s0, 7
	v_lshl_add_u64 v[2:3], s[2:3], 0, v[0:1]
	v_ashrrev_i32_e32 v0, 2, v12
	v_and_b32_e32 v44, 0xffffffe0, v0
	v_lshl_add_u64 v[2:3], v[2:3], 0, s[56:57]
	v_ashrrev_i32_e32 v45, 31, v44
	v_lshl_add_u64 v[60:61], v[44:45], 1, v[2:3]
	s_waitcnt lgkmcnt(0)
	s_barrier
	global_load_dwordx4 v[14:17], v[60:61], off
	s_lshl_b32 s1, s0, 8
	v_readlane_b32 s2, v255, 3
	s_add_u32 s2, s2, s1
	v_readlane_b32 s3, v255, 4
	s_addc_u32 s3, s3, 0
	v_lshlrev_b64 v[2:3], 2, v[44:45]
	v_lshl_add_u64 v[8:9], s[2:3], 0, v[2:3]
	v_readlane_b32 s2, v255, 5
	s_add_u32 s2, s2, s1
	v_readlane_b32 s1, v255, 6
	s_addc_u32 s3, s1, 0
	v_lshl_add_u64 v[10:11], s[2:3], 0, v[2:3]
	global_load_dwordx4 v[18:21], v[10:11], off
	global_load_dwordx4 v[22:25], v[8:9], off
	global_load_dwordx4 v[26:29], v[8:9], off offset:16
	global_load_dwordx4 v[30:33], v[10:11], off offset:16
	global_load_dwordx4 v[2:5], v[60:61], off offset:16
	global_load_dwordx4 v[36:39], v[8:9], off offset:32
	global_load_dwordx4 v[40:43], v[10:11], off offset:32
	v_lshlrev_b32_e32 v0, 2, v6
	v_lshlrev_b32_e32 v13, 1, v6
	s_movk_i32 s5, 0x110
	ds_read2st64_b32 v[6:7], v0 offset0:68 offset1:70
	v_sub_u32_e32 v0, v0, v13
	v_mul_lo_u32 v44, v44, s5
	v_add_u32_e32 v0, v0, v44
	v_or_b32_e32 v13, v44, v13
	global_load_dwordx4 v[44:47], v[8:9], off offset:48
	global_load_dwordx4 v[48:51], v[8:9], off offset:80
	global_load_dwordx4 v[52:55], v[8:9], off offset:64
	global_load_dwordx4 v[56:59], v[60:61], off offset:48
	s_nop 0
	global_load_dwordx4 v[60:63], v[60:61], off offset:32
	s_nop 0
	global_load_dwordx4 v[64:67], v[10:11], off offset:48
	global_load_dwordx4 v[68:71], v[10:11], off offset:80
	global_load_dwordx4 v[72:75], v[10:11], off offset:64
	s_or_b32 s0, s0, s39
	s_ashr_i32 s1, s0, 31
	s_lshl_b64 s[2:3], s[0:1], 7
	v_and_b32_e32 v34, 31, v12
	v_bfe_u32 v35, v12, 5, 1
	v_readlane_b32 s8, v253, 51
	v_readlane_b32 s10, v253, 53
	v_readlane_b32 s11, v253, 54
	s_lshl_b64 s[0:1], s[0:1], 9
	s_mov_b64 s[6:7], s[10:11]
	s_add_u32 s0, s6, s0
	s_addc_u32 s1, s7, s1
	v_readlane_b32 s9, v253, 52
	v_readlane_b32 s12, v253, 55
	v_readlane_b32 s13, v253, 56
	v_readlane_b32 s14, v253, 57
	v_readlane_b32 s15, v253, 58
	v_readlane_b32 s16, v253, 59
	v_readlane_b32 s17, v253, 60
	v_readlane_b32 s18, v253, 61
	v_readlane_b32 s19, v253, 62
	v_readlane_b32 s20, v253, 63
	v_readlane_b32 s21, v254, 0
	v_readlane_b32 s22, v254, 1
	v_readlane_b32 s23, v254, 2
	s_mov_b64 s[6:7], -1
	s_waitcnt vmcnt(15)
	v_lshlrev_b32_e32 v76, 16, v14
	v_and_b32_e32 v14, 0xffff0000, v14
	v_lshlrev_b32_e32 v77, 16, v15
	v_and_b32_e32 v15, 0xffff0000, v15
	v_lshlrev_b32_e32 v78, 16, v16
	v_and_b32_e32 v16, 0xffff0000, v16
	s_waitcnt lgkmcnt(0)
	v_sub_f32_e32 v76, v76, v6
	v_sub_f32_e32 v14, v14, v6
	v_sub_f32_e32 v77, v77, v6
	v_sub_f32_e32 v15, v15, v6
	v_sub_f32_e32 v78, v78, v6
	v_sub_f32_e32 v16, v16, v6
	v_mul_f32_e32 v76, v7, v76
	v_mul_f32_e32 v14, v7, v14
	v_mul_f32_e32 v77, v7, v77
	v_mul_f32_e32 v15, v7, v15
	v_mul_f32_e32 v78, v7, v78
	v_mul_f32_e32 v16, v7, v16
	s_waitcnt vmcnt(13)
	v_fma_f32 v18, v22, v76, v18
	v_fma_f32 v14, v23, v14, v19
	v_fma_f32 v19, v77, v24, v20
	v_fmac_f32_e32 v21, v15, v25
	s_waitcnt vmcnt(11)
	v_fma_f32 v15, v78, v26, v30
	v_fma_f32 v16, v16, v27, v31
	v_bfe_u32 v22, v18, 16, 1
	v_bfe_u32 v23, v14, 16, 1
	v_lshlrev_b32_e32 v79, 16, v17
	v_bfe_u32 v24, v19, 16, 1
	v_bfe_u32 v25, v21, 16, 1
	v_bfe_u32 v26, v15, 16, 1
	v_bfe_u32 v27, v16, 16, 1
	v_add3_u32 v18, v18, v22, s37
	v_add3_u32 v14, v14, v23, s37
	v_sub_f32_e32 v79, v79, v6
	v_add3_u32 v19, v19, v24, s37
	v_add3_u32 v21, v21, v25, s37
	v_add3_u32 v15, v15, v26, s37
	v_add3_u32 v16, v16, v27, s37
	ds_write_b16_d16_hi v0, v18
	ds_write_b16_d16_hi v13, v14 offset:272
	ds_write_b16_d16_hi v0, v19 offset:544
	ds_write_b16_d16_hi v13, v21 offset:816
	ds_write_b16_d16_hi v0, v15 offset:1088
	ds_write_b16_d16_hi v13, v16 offset:1360
	v_and_b32_e32 v14, 0xffff0000, v17
	v_mul_f32_e32 v79, v7, v79
	v_sub_f32_e32 v14, v14, v6
	v_fma_f32 v20, v79, v28, v32
	v_mul_f32_e32 v14, v7, v14
	v_fmac_f32_e32 v33, v14, v29
	v_bfe_u32 v14, v20, 16, 1
	v_add3_u32 v14, v20, v14, s37
	ds_write_b16_d16_hi v0, v14 offset:1632
	v_bfe_u32 v14, v33, 16, 1
	v_add3_u32 v14, v33, v14, s37
	ds_write_b16_d16_hi v13, v14 offset:1904
	s_waitcnt vmcnt(10)
	v_lshlrev_b32_e32 v14, 16, v2
	v_sub_f32_e32 v14, v14, v6
	v_mul_f32_e32 v14, v7, v14
	v_and_b32_e32 v2, 0xffff0000, v2
	s_waitcnt vmcnt(8)
	v_fma_f32 v14, v36, v14, v40
	v_sub_f32_e32 v2, v2, v6
	v_mul_f32_e32 v2, v7, v2
	v_bfe_u32 v15, v14, 16, 1
	v_fma_f32 v2, v37, v2, v41
	v_add3_u32 v14, v14, v15, s37
	ds_write_b16_d16_hi v0, v14 offset:2176
	v_bfe_u32 v14, v2, 16, 1
	v_add3_u32 v2, v2, v14, s37
	ds_write_b16_d16_hi v13, v2 offset:2448
	v_lshlrev_b32_e32 v2, 16, v3
	v_sub_f32_e32 v2, v2, v6
	v_and_b32_e32 v3, 0xffff0000, v3
	v_mul_f32_e32 v2, v7, v2
	v_sub_f32_e32 v3, v3, v6
	v_fma_f32 v2, v2, v38, v42
	v_mul_f32_e32 v3, v7, v3
	v_fmac_f32_e32 v43, v3, v39
	v_bfe_u32 v3, v2, 16, 1
	v_add3_u32 v2, v2, v3, s37
	ds_write_b16_d16_hi v0, v2 offset:2720
	v_bfe_u32 v2, v43, 16, 1
	v_add3_u32 v2, v43, v2, s37
	ds_write_b16_d16_hi v13, v2 offset:2992
	global_load_dwordx4 v[14:17], v[8:9], off offset:112
	global_load_dwordx4 v[18:21], v[8:9], off offset:96
	global_load_dwordx4 v[22:25], v[10:11], off offset:112
	s_nop 0
	global_load_dwordx4 v[8:11], v[10:11], off offset:96
	v_lshlrev_b32_e32 v2, 16, v4
	v_sub_f32_e32 v2, v2, v6
	v_mul_f32_e32 v2, v7, v2
	v_and_b32_e32 v3, 0xffff0000, v4
	s_waitcnt vmcnt(6)
	v_fma_f32 v2, v2, v44, v64
	v_sub_f32_e32 v3, v3, v6
	v_mul_f32_e32 v3, v7, v3
	v_bfe_u32 v4, v2, 16, 1
	v_fma_f32 v3, v3, v45, v65
	v_add3_u32 v2, v2, v4, s37
	ds_write_b16_d16_hi v0, v2 offset:3264
	v_bfe_u32 v2, v3, 16, 1
	v_add3_u32 v2, v3, v2, s37
	ds_write_b16_d16_hi v13, v2 offset:3536
	v_lshlrev_b32_e32 v2, 16, v5
	v_sub_f32_e32 v2, v2, v6
	v_and_b32_e32 v3, 0xffff0000, v5
	v_mul_f32_e32 v2, v7, v2
	v_sub_f32_e32 v3, v3, v6
	v_fma_f32 v2, v2, v46, v66
	v_mul_f32_e32 v3, v7, v3
	v_fmac_f32_e32 v67, v3, v47
	v_bfe_u32 v3, v2, 16, 1
	v_add3_u32 v2, v2, v3, s37
	ds_write_b16_d16_hi v0, v2 offset:3808
	v_bfe_u32 v2, v67, 16, 1
	v_add3_u32 v2, v67, v2, s37
	ds_write_b16_d16_hi v13, v2 offset:4080
	v_lshlrev_b32_e32 v2, 16, v60
	v_sub_f32_e32 v2, v2, v6
	v_mul_f32_e32 v2, v7, v2
	v_and_b32_e32 v3, 0xffff0000, v60
	s_waitcnt vmcnt(4)
	v_fma_f32 v2, v52, v2, v72
	v_sub_f32_e32 v3, v3, v6
	v_mul_f32_e32 v3, v7, v3
	v_bfe_u32 v4, v2, 16, 1
	v_fma_f32 v3, v53, v3, v73
	v_add3_u32 v2, v2, v4, s37
	ds_write_b16_d16_hi v0, v2 offset:4352
	v_bfe_u32 v2, v3, 16, 1
	v_add3_u32 v2, v3, v2, s37
	ds_write_b16_d16_hi v13, v2 offset:4624
	v_lshlrev_b32_e32 v2, 16, v61
	v_sub_f32_e32 v2, v2, v6
	v_and_b32_e32 v3, 0xffff0000, v61
	v_mul_f32_e32 v2, v7, v2
	v_sub_f32_e32 v3, v3, v6
	v_fma_f32 v2, v2, v54, v74
	v_mul_f32_e32 v3, v7, v3
	v_fmac_f32_e32 v75, v3, v55
	v_bfe_u32 v3, v2, 16, 1
	v_add3_u32 v2, v2, v3, s37
	ds_write_b16_d16_hi v0, v2 offset:4896
	v_bfe_u32 v2, v75, 16, 1
	v_add3_u32 v2, v75, v2, s37
	ds_write_b16_d16_hi v13, v2 offset:5168
	v_lshlrev_b32_e32 v2, 16, v62
	v_sub_f32_e32 v2, v2, v6
	v_mul_f32_e32 v2, v7, v2
	v_and_b32_e32 v3, 0xffff0000, v62
	v_fma_f32 v2, v2, v48, v68
	v_sub_f32_e32 v3, v3, v6
	v_mul_f32_e32 v3, v7, v3
	v_bfe_u32 v4, v2, 16, 1
	v_fma_f32 v3, v3, v49, v69
	v_add3_u32 v2, v2, v4, s37
	ds_write_b16_d16_hi v0, v2 offset:5440
	v_bfe_u32 v2, v3, 16, 1
	v_add3_u32 v2, v3, v2, s37
	ds_write_b16_d16_hi v13, v2 offset:5712
	v_lshlrev_b32_e32 v2, 16, v63
	v_sub_f32_e32 v2, v2, v6
	v_and_b32_e32 v3, 0xffff0000, v63
	v_mul_f32_e32 v2, v7, v2
	v_sub_f32_e32 v3, v3, v6
	v_fma_f32 v2, v2, v50, v70
	v_mul_f32_e32 v3, v7, v3
	v_fmac_f32_e32 v71, v3, v51
	v_bfe_u32 v3, v2, 16, 1
	v_add3_u32 v2, v2, v3, s37
	ds_write_b16_d16_hi v0, v2 offset:5984
	v_bfe_u32 v2, v71, 16, 1
	v_add3_u32 v2, v71, v2, s37
	ds_write_b16_d16_hi v13, v2 offset:6256
	v_lshlrev_b32_e32 v2, 16, v56
	v_sub_f32_e32 v2, v2, v6
	v_mul_f32_e32 v2, v7, v2
	v_and_b32_e32 v3, 0xffff0000, v56
	s_waitcnt vmcnt(0)
	v_fma_f32 v2, v18, v2, v8
	v_sub_f32_e32 v3, v3, v6
	v_mul_f32_e32 v3, v7, v3
	v_bfe_u32 v4, v2, 16, 1
	v_fma_f32 v3, v19, v3, v9
	v_add3_u32 v2, v2, v4, s37
	ds_write_b16_d16_hi v0, v2 offset:6528
	v_bfe_u32 v2, v3, 16, 1
	v_add3_u32 v2, v3, v2, s37
	ds_write_b16_d16_hi v13, v2 offset:6800
	v_lshlrev_b32_e32 v2, 16, v57
	v_sub_f32_e32 v2, v2, v6
	v_and_b32_e32 v3, 0xffff0000, v57
	v_mul_f32_e32 v2, v7, v2
	v_sub_f32_e32 v3, v3, v6
	v_fma_f32 v2, v2, v20, v10
	v_mul_f32_e32 v3, v7, v3
	v_fmac_f32_e32 v11, v3, v21
	v_bfe_u32 v3, v2, 16, 1
	v_add3_u32 v2, v2, v3, s37
	ds_write_b16_d16_hi v0, v2 offset:7072
	v_bfe_u32 v2, v11, 16, 1
	v_add3_u32 v2, v11, v2, s37
	ds_write_b16_d16_hi v13, v2 offset:7344
	v_lshlrev_b32_e32 v2, 16, v58
	v_sub_f32_e32 v2, v2, v6
	v_mul_f32_e32 v2, v7, v2
	v_and_b32_e32 v3, 0xffff0000, v58
	v_fma_f32 v2, v2, v14, v22
	v_sub_f32_e32 v3, v3, v6
	v_mul_f32_e32 v3, v7, v3
	v_bfe_u32 v4, v2, 16, 1
	v_fma_f32 v3, v3, v15, v23
	v_add3_u32 v2, v2, v4, s37
	ds_write_b16_d16_hi v0, v2 offset:7616
	v_bfe_u32 v2, v3, 16, 1
	v_add3_u32 v2, v3, v2, s37
	ds_write_b16_d16_hi v13, v2 offset:7888
	v_lshlrev_b32_e32 v2, 16, v59
	v_sub_f32_e32 v2, v2, v6
	v_and_b32_e32 v3, 0xffff0000, v59
	v_mul_f32_e32 v2, v7, v2
	v_sub_f32_e32 v3, v3, v6
	v_fma_f32 v2, v2, v16, v24
	v_mul_f32_e32 v3, v7, v3
	v_fmac_f32_e32 v25, v3, v17
	v_bfe_u32 v3, v2, 16, 1
	v_add3_u32 v2, v2, v3, s37
	ds_write_b16_d16_hi v0, v2 offset:8160
	v_bfe_u32 v0, v25, 16, 1
	v_add3_u32 v0, v25, v0, s37
	ds_write_b16_d16_hi v13, v0 offset:8432
	v_ashrrev_i32_e32 v0, 1, v12
	v_and_b32_e32 v56, 0xffffffe0, v0
	v_ashrrev_i32_e32 v57, 31, v56
	v_lshl_add_u64 v[2:3], s[2:3], 0, v[56:57]
	v_or_b32_e32 v2, v2, v34
	v_readlane_b32 s2, v250, 52
	v_lshlrev_b64 v[2:3], 8, v[2:3]
	v_readlane_b32 s3, v250, 53
	v_lshlrev_b32_e32 v0, 4, v35
	s_waitcnt lgkmcnt(0)
	v_lshl_add_u64 v[2:3], s[2:3], 0, v[2:3]
	v_lshl_add_u64 v[62:63], v[2:3], 0, v[0:1]
	s_barrier
	global_load_dwordx4 v[18:21], v[62:63], off
	global_load_dwordx4 v[36:39], v[62:63], off offset:32
	v_mad_u32_u24 v66, v34, s5, v0
	ds_read_b128 v[2:5], v66
	ds_read_b128 v[40:43], v66 offset:32
	s_waitcnt vmcnt(1) lgkmcnt(1)
	v_mfma_f32_32x32x16_bf16 v[2:17], v[18:21], v[2:5], 0
	ds_read_b128 v[22:25], v66 offset:8704
	ds_read_b128 v[44:47], v66 offset:8736
	v_readlane_b32 s2, v251, 27
	s_add_u32 s2, s2, s56
	v_readlane_b32 s3, v251, 28
	s_addc_u32 s3, s3, 0
	v_lshlrev_b32_e32 v0, 1, v34
	s_waitcnt vmcnt(0) lgkmcnt(2)
	v_mfma_f32_32x32x16_bf16 v[2:17], v[36:39], v[40:43], v[2:17]
	global_load_dwordx4 v[40:43], v[62:63], off offset:64
	s_waitcnt lgkmcnt(1)
	v_mfma_f32_32x32x16_bf16 v[18:33], v[18:21], v[22:25], 0
	s_waitcnt lgkmcnt(0)
	v_mfma_f32_32x32x16_bf16 v[18:33], v[36:39], v[44:47], v[18:33]
	global_load_dwordx4 v[36:39], v[62:63], off offset:96
	ds_read_b128 v[44:47], v66 offset:64
	ds_read_b128 v[48:51], v66 offset:96
	s_waitcnt vmcnt(1) lgkmcnt(1)
	v_mfma_f32_32x32x16_bf16 v[2:17], v[40:43], v[44:47], v[2:17]
	ds_read_b128 v[44:47], v66 offset:8768
	ds_read_b128 v[52:55], v66 offset:8800
	s_waitcnt lgkmcnt(1)
	v_mfma_f32_32x32x16_bf16 v[18:33], v[40:43], v[44:47], v[18:33]
	global_load_dwordx4 v[40:43], v[62:63], off offset:128
	s_waitcnt vmcnt(1)
	v_mfma_f32_32x32x16_bf16 v[2:17], v[36:39], v[48:51], v[2:17]
	s_waitcnt lgkmcnt(0)
	v_mfma_f32_32x32x16_bf16 v[18:33], v[36:39], v[52:55], v[18:33]
	global_load_dwordx4 v[36:39], v[62:63], off offset:160
	ds_read_b128 v[44:47], v66 offset:128
	ds_read_b128 v[48:51], v66 offset:160
	s_waitcnt vmcnt(1) lgkmcnt(1)
	v_mfma_f32_32x32x16_bf16 v[2:17], v[40:43], v[44:47], v[2:17]
	ds_read_b128 v[44:47], v66 offset:8832
	ds_read_b128 v[52:55], v66 offset:8864
	global_load_dwordx4 v[58:61], v[62:63], off offset:192
	s_waitcnt lgkmcnt(1)
	v_mfma_f32_32x32x16_bf16 v[18:33], v[40:43], v[44:47], v[18:33]
	ds_read_b128 v[42:45], v66 offset:224
	s_waitcnt vmcnt(1)
	v_mfma_f32_32x32x16_bf16 v[2:17], v[36:39], v[48:51], v[2:17]
	ds_read_b128 v[46:49], v66 offset:192
	s_waitcnt lgkmcnt(2)
	v_mfma_f32_32x32x16_bf16 v[18:33], v[36:39], v[52:55], v[18:33]
	global_load_dwordx4 v[38:41], v[62:63], off offset:224
	v_lshl_or_b32 v36, v35, 2, v56
	v_add_u32_e32 v50, s4, v36
	v_ashrrev_i32_e32 v51, 31, v50
	v_lshl_add_u64 v[52:53], s[2:3], 0, v[0:1]
	v_ashrrev_i32_e32 v37, 31, v36
	v_lshl_add_u64 v[54:55], v[36:37], 2, s[0:1]
	s_waitcnt vmcnt(1) lgkmcnt(0)
	v_mfma_f32_32x32x16_bf16 v[2:17], v[58:61], v[46:49], v[2:17]
	v_lshlrev_b64 v[46:47], 9, v[50:51]
	v_lshl_add_u64 v[56:57], v[52:53], 0, v[46:47]
	global_load_ushort v67, v[56:57], off
	global_load_dwordx4 v[34:37], v[54:55], off
	ds_read_b128 v[62:65], v66 offset:8896
	ds_read_b128 v[46:49], v66 offset:8928
	s_add_u32 s0, s94, s56
	s_addc_u32 s1, s95, 0
	s_waitcnt lgkmcnt(1)
	v_mfma_f32_32x32x16_bf16 v[18:33], v[58:61], v[62:65], v[18:33]
	global_load_ushort v64, v[56:57], off offset:64
	s_mov_b32 s98, 0x1000
	s_mov_b32 s99, 0
	v_lshl_add_u64 v[100:101], v[56:57], 0, s[98:99]
	v_lshl_add_u64 v[102:103], v[100:101], 0, s[98:99]
	v_lshl_add_u64 v[104:105], v[102:103], 0, s[98:99]
	global_load_ushort v68, v[56:57], off offset:512
	global_load_ushort v69, v[56:57], off offset:576
	global_load_ushort v70, v[56:57], off offset:1024
	global_load_ushort v71, v[56:57], off offset:1088
	global_load_ushort v72, v[56:57], off offset:1536
	global_load_ushort v73, v[56:57], off offset:1600
	global_load_ushort v74, v[100:101], off
	global_load_ushort v75, v[100:101], off offset:64
	global_load_ushort v76, v[100:101], off offset:512
	global_load_ushort v77, v[100:101], off offset:576
	global_load_ushort v78, v[100:101], off offset:1024
	global_load_ushort v79, v[100:101], off offset:1088
	global_load_ushort v80, v[100:101], off offset:1536
	global_load_ushort v81, v[100:101], off offset:1600
	global_load_ushort v82, v[102:103], off
	global_load_ushort v83, v[102:103], off offset:64
	global_load_ushort v84, v[102:103], off offset:512
	global_load_ushort v85, v[102:103], off offset:576
	global_load_ushort v86, v[102:103], off offset:1024
	global_load_ushort v87, v[102:103], off offset:1088
	global_load_ushort v88, v[102:103], off offset:1536
	global_load_ushort v89, v[102:103], off offset:1600
	global_load_ushort v90, v[104:105], off
	global_load_ushort v91, v[104:105], off offset:64
	global_load_ushort v92, v[104:105], off offset:512
	global_load_ushort v93, v[104:105], off offset:576
	global_load_ushort v94, v[104:105], off offset:1024
	global_load_ushort v95, v[104:105], off offset:1088
	global_load_ushort v96, v[104:105], off offset:1536
	global_load_ushort v97, v[104:105], off offset:1600
	global_load_dwordx4 v[106:109], v[54:55], off offset:32
	global_load_dwordx4 v[110:113], v[54:55], off offset:64
	global_load_dwordx4 v[114:117], v[54:55], off offset:96
	v_add_u32_e32 v60, 1, v50
	v_ashrrev_i32_e32 v61, 31, v60
	v_lshlrev_b64 v[62:63], 9, v[60:61]
	v_lshl_add_u64 v[62:63], v[52:53], 0, v[62:63]
	s_waitcnt vmcnt(3)
	v_mfma_f32_32x32x16_bf16 v[2:17], v[38:41], v[42:45], v[2:17]
	v_lshl_add_u64 v[42:43], s[0:1], 0, v[0:1]
	v_lshlrev_b64 v[44:45], 11, v[50:51]
	v_lshl_add_u64 v[44:45], v[42:43], 0, v[44:45]
	v_add_co_u32_e32 v44, vcc, s35, v44
	s_waitcnt vmcnt(2)
	v_lshlrev_b32_e32 v0, 16, v67
	s_waitcnt lgkmcnt(0)
	v_mfma_f32_32x32x16_bf16 v[18:33], v[38:41], v[46:49], v[18:33]
	s_waitcnt vmcnt(1)
	s_nop 2
	v_add_f32_e32 v2, v2, v34
	v_mul_f32_e32 v0, v2, v0
	v_bfe_u32 v2, v0, 16, 1
	v_add3_u32 v0, v0, v2, s37
	v_addc_co_u32_e32 v45, vcc, 0, v45, vcc
	global_store_short_d16_hi v[44:45], v0, off offset:1792
	s_waitcnt vmcnt(0)
	v_mov_b32_e32 v0, v68
	v_lshlrev_b32_e32 v2, 16, v64
	v_add_f32_e32 v18, v18, v34
	v_mul_f32_e32 v2, v18, v2
	v_bfe_u32 v18, v2, 16, 1
	v_add3_u32 v2, v2, v18, s37
	global_store_short_d16_hi v[44:45], v2, off offset:1856
	v_mov_b32_e32 v18, v69
	v_add_f32_e32 v2, v3, v35
	v_add_u32_e32 v38, 2, v50
	v_ashrrev_i32_e32 v39, 31, v38
	v_lshlrev_b64 v[40:41], 9, v[38:39]
	v_lshl_add_u64 v[40:41], v[52:53], 0, v[40:41]
	v_add_f32_e32 v19, v19, v35
	v_add_f32_e32 v4, v4, v36
	v_mov_b64_e32 v[56:57], v[106:107]
	v_mov_b64_e32 v[58:59], v[108:109]
	v_add_f32_e32 v5, v5, v37
	v_lshlrev_b32_e32 v0, 16, v0
	v_mul_f32_e32 v0, v2, v0
	v_bfe_u32 v2, v0, 16, 1
	v_add3_u32 v0, v0, v2, s37
	v_lshlrev_b64 v[2:3], 11, v[60:61]
	v_lshl_add_u64 v[2:3], v[42:43], 0, v[2:3]
	v_add_co_u32_e32 v2, vcc, s35, v2
	v_lshlrev_b32_e32 v18, 16, v18
	v_addc_co_u32_e32 v3, vcc, 0, v3, vcc
	global_store_short_d16_hi v[2:3], v0, off offset:1792
	v_mov_b32_e32 v0, v70
	v_mul_f32_e32 v18, v19, v18
	v_bfe_u32 v19, v18, 16, 1
	v_add3_u32 v18, v18, v19, s37
	global_store_short_d16_hi v[2:3], v18, off offset:1856
	v_mov_b32_e32 v40, v71
	v_lshlrev_b64 v[18:19], 11, v[38:39]
	v_lshl_add_u64 v[18:19], v[42:43], 0, v[18:19]
	v_add_co_u32_e32 v18, vcc, s35, v18
	v_add_u32_e32 v2, 3, v50
	s_nop 0
	v_addc_co_u32_e32 v19, vcc, 0, v19, vcc
	v_ashrrev_i32_e32 v3, 31, v2
	v_lshlrev_b64 v[34:35], 9, v[2:3]
	v_lshl_add_u64 v[34:35], v[52:53], 0, v[34:35]
	v_lshlrev_b64 v[2:3], 11, v[2:3]
	v_lshl_add_u64 v[2:3], v[42:43], 0, v[2:3]
	v_add_co_u32_e32 v2, vcc, s35, v2
	v_add_f32_e32 v6, v6, v56
	v_addc_co_u32_e32 v3, vcc, 0, v3, vcc
	v_add_f32_e32 v7, v7, v57
	v_add_f32_e32 v8, v8, v58
	v_add_f32_e32 v9, v9, v59
	v_lshlrev_b32_e32 v0, 16, v0
	v_mul_f32_e32 v0, v4, v0
	v_bfe_u32 v4, v0, 16, 1
	v_add3_u32 v0, v0, v4, s37
	global_store_short_d16_hi v[18:19], v0, off offset:1792
	v_lshlrev_b32_e32 v0, 16, v40
	v_add_f32_e32 v4, v20, v36
	v_mul_f32_e32 v0, v4, v0
	v_bfe_u32 v4, v0, 16, 1
	v_add3_u32 v0, v0, v4, s37
	global_store_short_d16_hi v[18:19], v0, off offset:1856
	v_mov_b32_e32 v0, v72
	s_nop 0
	v_mov_b32_e32 v4, v73
	v_add_u32_e32 v18, 8, v50
	v_add_f32_e32 v20, v21, v37
	v_ashrrev_i32_e32 v19, 31, v18
	v_lshlrev_b64 v[34:35], 9, v[18:19]
	v_lshl_add_u64 v[34:35], v[52:53], 0, v[34:35]
	v_add_f32_e32 v21, v22, v56
	v_add_f32_e32 v22, v25, v59
	v_lshlrev_b32_e32 v0, 16, v0
	v_lshlrev_b32_e32 v4, 16, v4
	v_mul_f32_e32 v0, v5, v0
	v_mul_f32_e32 v4, v20, v4
	v_bfe_u32 v5, v0, 16, 1
	v_bfe_u32 v20, v4, 16, 1
	v_add3_u32 v0, v0, v5, s37
	v_add3_u32 v4, v4, v20, s37
	global_store_short_d16_hi v[2:3], v0, off offset:1792
	global_store_short_d16_hi v[2:3], v4, off offset:1856
	v_mov_b32_e32 v0, v74
	s_nop 0
	v_mov_b32_e32 v20, v75
	v_lshlrev_b64 v[4:5], 11, v[18:19]
	v_add_u32_e32 v2, 9, v50
	v_lshl_add_u64 v[4:5], v[42:43], 0, v[4:5]
	v_ashrrev_i32_e32 v3, 31, v2
	v_add_co_u32_e32 v4, vcc, s35, v4
	v_lshlrev_b64 v[18:19], 9, v[2:3]
	s_nop 0
	v_addc_co_u32_e32 v5, vcc, 0, v5, vcc
	v_lshl_add_u64 v[18:19], v[52:53], 0, v[18:19]
	v_lshlrev_b64 v[2:3], 11, v[2:3]
	v_lshl_add_u64 v[2:3], v[42:43], 0, v[2:3]
	v_add_co_u32_e32 v2, vcc, s35, v2
	v_lshlrev_b32_e32 v0, 16, v0
	v_lshlrev_b32_e32 v20, 16, v20
	v_mul_f32_e32 v0, v6, v0
	v_mul_f32_e32 v6, v21, v20
	v_bfe_u32 v20, v0, 16, 1
	v_bfe_u32 v21, v6, 16, 1
	v_add3_u32 v0, v0, v20, s37
	v_add3_u32 v6, v6, v21, s37
	global_store_short_d16_hi v[4:5], v0, off offset:1792
	global_store_short_d16_hi v[4:5], v6, off offset:1856
	v_mov_b32_e32 v0, v76
	s_nop 0
	v_mov_b32_e32 v6, v77
	v_add_u32_e32 v4, 10, v50
	v_add_f32_e32 v20, v23, v57
	v_ashrrev_i32_e32 v5, 31, v4
	v_lshlrev_b64 v[18:19], 9, v[4:5]
	v_addc_co_u32_e32 v3, vcc, 0, v3, vcc
	v_lshl_add_u64 v[18:19], v[52:53], 0, v[18:19]
	v_lshlrev_b64 v[4:5], 11, v[4:5]
	v_lshl_add_u64 v[4:5], v[42:43], 0, v[4:5]
	v_add_co_u32_e32 v4, vcc, s35, v4
	v_lshlrev_b32_e32 v0, 16, v0
	v_lshlrev_b32_e32 v6, 16, v6
	v_mul_f32_e32 v0, v7, v0
	v_mul_f32_e32 v6, v20, v6
	v_bfe_u32 v7, v0, 16, 1
	v_bfe_u32 v20, v6, 16, 1
	v_add3_u32 v0, v0, v7, s37
	v_add3_u32 v6, v6, v20, s37
	global_store_short_d16_hi v[2:3], v0, off offset:1792
	global_store_short_d16_hi v[2:3], v6, off offset:1856
	v_mov_b32_e32 v0, v78
	s_nop 0
	v_mov_b32_e32 v18, v79
	v_add_u32_e32 v2, 11, v50
	v_add_f32_e32 v19, v24, v58
	v_ashrrev_i32_e32 v3, 31, v2
	v_lshlrev_b64 v[6:7], 9, v[2:3]
	v_addc_co_u32_e32 v5, vcc, 0, v5, vcc
	v_lshl_add_u64 v[6:7], v[52:53], 0, v[6:7]
	v_lshlrev_b64 v[2:3], 11, v[2:3]
	v_lshl_add_u64 v[2:3], v[42:43], 0, v[2:3]
	v_add_co_u32_e32 v20, vcc, s35, v2
	v_lshlrev_b32_e32 v0, 16, v0
	v_lshlrev_b32_e32 v18, 16, v18
	v_mul_f32_e32 v0, v8, v0
	v_mul_f32_e32 v8, v19, v18
	v_bfe_u32 v18, v0, 16, 1
	v_bfe_u32 v19, v8, 16, 1
	v_add3_u32 v0, v0, v18, s37
	v_add3_u32 v8, v8, v19, s37
	global_store_short_d16_hi v[4:5], v0, off offset:1792
	global_store_short_d16_hi v[4:5], v8, off offset:1856
	v_mov_b32_e32 v0, v80
	s_nop 0
	v_mov_b32_e32 v8, v81
	v_add_u32_e32 v6, 16, v50
	v_ashrrev_i32_e32 v7, 31, v6
	v_lshlrev_b64 v[4:5], 9, v[6:7]
	v_addc_co_u32_e32 v21, vcc, 0, v3, vcc
	v_lshl_add_u64 v[18:19], v[52:53], 0, v[4:5]
	v_mov_b64_e32 v[2:3], v[110:111]
	v_mov_b64_e32 v[4:5], v[112:113]
	v_lshlrev_b64 v[6:7], 11, v[6:7]
	v_lshl_add_u64 v[6:7], v[42:43], 0, v[6:7]
	v_lshlrev_b32_e32 v0, 16, v0
	v_lshlrev_b32_e32 v8, 16, v8
	v_mul_f32_e32 v0, v9, v0
	v_mul_f32_e32 v8, v22, v8
	v_bfe_u32 v9, v0, 16, 1
	v_bfe_u32 v22, v8, 16, 1
	v_add3_u32 v0, v0, v9, s37
	v_add3_u32 v8, v8, v22, s37
	global_store_short_d16_hi v[20:21], v0, off offset:1792
	global_store_short_d16_hi v[20:21], v8, off offset:1856
	v_mov_b32_e32 v0, v82
	s_nop 0
	v_mov_b32_e32 v24, v83
	v_add_f32_e32 v10, v10, v2
	v_add_u32_e32 v18, 17, v50
	v_add_f32_e32 v2, v26, v2
	v_ashrrev_i32_e32 v19, 31, v18
	v_add_co_u32_e32 v22, vcc, s35, v6
	v_lshlrev_b64 v[8:9], 9, v[18:19]
	s_nop 0
	v_addc_co_u32_e32 v23, vcc, 0, v7, vcc
	v_lshl_add_u64 v[20:21], v[52:53], 0, v[8:9]
	v_mov_b64_e32 v[6:7], v[114:115]
	v_mov_b64_e32 v[8:9], v[116:117]
	v_lshlrev_b64 v[18:19], 11, v[18:19]
	v_lshl_add_u64 v[18:19], v[42:43], 0, v[18:19]
	v_add_co_u32_e32 v18, vcc, s35, v18
	v_add_f32_e32 v12, v12, v4
	s_nop 0
	v_addc_co_u32_e32 v19, vcc, 0, v19, vcc
	v_add_f32_e32 v4, v28, v4
	v_lshlrev_b32_e32 v0, 16, v0
	v_lshlrev_b32_e32 v24, 16, v24
	v_mul_f32_e32 v0, v10, v0
	v_mul_f32_e32 v2, v2, v24
	v_bfe_u32 v10, v0, 16, 1
	v_bfe_u32 v24, v2, 16, 1
	v_add3_u32 v0, v0, v10, s37
	v_add3_u32 v2, v2, v24, s37
	global_store_short_d16_hi v[22:23], v0, off offset:1792
	global_store_short_d16_hi v[22:23], v2, off offset:1856
	v_mov_b32_e32 v0, v84
	s_nop 0
	v_mov_b32_e32 v2, v85
	v_add_f32_e32 v10, v11, v3
	v_add_u32_e32 v20, 18, v50
	v_add_f32_e32 v3, v27, v3
	v_ashrrev_i32_e32 v21, 31, v20
	v_lshlrev_b64 v[22:23], 9, v[20:21]
	v_lshl_add_u64 v[22:23], v[52:53], 0, v[22:23]
	v_lshlrev_b32_e32 v0, 16, v0
	v_lshlrev_b32_e32 v2, 16, v2
	v_mul_f32_e32 v0, v10, v0
	v_mul_f32_e32 v2, v3, v2
	v_bfe_u32 v3, v0, 16, 1
	v_bfe_u32 v10, v2, 16, 1
	v_add3_u32 v0, v0, v3, s37
	v_add3_u32 v2, v2, v10, s37
	global_store_short_d16_hi v[18:19], v0, off offset:1792
	global_store_short_d16_hi v[18:19], v2, off offset:1856
	v_mov_b32_e32 v0, v86
	s_nop 0
	v_mov_b32_e32 v22, v87
	v_lshlrev_b64 v[10:11], 11, v[20:21]
	v_add_u32_e32 v2, 19, v50
	v_lshl_add_u64 v[10:11], v[42:43], 0, v[10:11]
	v_ashrrev_i32_e32 v3, 31, v2
	v_add_co_u32_e32 v10, vcc, s35, v10
	v_lshlrev_b64 v[18:19], 9, v[2:3]
	s_nop 0
	v_addc_co_u32_e32 v11, vcc, 0, v11, vcc
	v_lshl_add_u64 v[18:19], v[52:53], 0, v[18:19]
	v_lshlrev_b64 v[2:3], 11, v[2:3]
	v_lshl_add_u64 v[2:3], v[42:43], 0, v[2:3]
	v_add_co_u32_e32 v2, vcc, s35, v2
	v_lshlrev_b32_e32 v0, 16, v0
	v_lshlrev_b32_e32 v20, 16, v22
	v_mul_f32_e32 v0, v12, v0
	v_mul_f32_e32 v4, v4, v20
	v_bfe_u32 v12, v0, 16, 1
	v_bfe_u32 v20, v4, 16, 1
	v_add3_u32 v0, v0, v12, s37
	v_add3_u32 v4, v4, v20, s37
	global_store_short_d16_hi v[10:11], v0, off offset:1792
	global_store_short_d16_hi v[10:11], v4, off offset:1856
	v_mov_b32_e32 v0, v88
	s_nop 0
	v_mov_b32_e32 v4, v89
	v_add_f32_e32 v12, v13, v5
	v_add_u32_e32 v10, 24, v50
	v_add_f32_e32 v5, v29, v5
	v_ashrrev_i32_e32 v11, 31, v10
	v_lshlrev_b64 v[18:19], 9, v[10:11]
	v_addc_co_u32_e32 v3, vcc, 0, v3, vcc
	v_lshl_add_u64 v[18:19], v[52:53], 0, v[18:19]
	v_add_f32_e32 v13, v14, v6
	v_add_f32_e32 v6, v30, v6
	v_lshlrev_b32_e32 v0, 16, v0
	v_lshlrev_b32_e32 v4, 16, v4
	v_mul_f32_e32 v0, v12, v0
	v_mul_f32_e32 v4, v5, v4
	v_bfe_u32 v5, v0, 16, 1
	v_bfe_u32 v12, v4, 16, 1
	v_add3_u32 v0, v0, v5, s37
	v_add3_u32 v4, v4, v12, s37
	global_store_short_d16_hi v[2:3], v0, off offset:1792
	global_store_short_d16_hi v[2:3], v4, off offset:1856
	v_mov_b32_e32 v0, v90
	s_nop 0
	v_mov_b32_e32 v12, v91
	v_lshlrev_b64 v[4:5], 11, v[10:11]
	v_add_u32_e32 v2, 25, v50
	v_lshl_add_u64 v[4:5], v[42:43], 0, v[4:5]
	v_ashrrev_i32_e32 v3, 31, v2
	v_add_co_u32_e32 v4, vcc, s35, v4
	v_lshlrev_b64 v[10:11], 9, v[2:3]
	s_nop 0
	v_addc_co_u32_e32 v5, vcc, 0, v5, vcc
	v_lshl_add_u64 v[10:11], v[52:53], 0, v[10:11]
	v_lshlrev_b64 v[2:3], 11, v[2:3]
	v_lshl_add_u64 v[2:3], v[42:43], 0, v[2:3]
	v_add_co_u32_e32 v2, vcc, s35, v2
	v_lshlrev_b32_e32 v0, 16, v0
	v_lshlrev_b32_e32 v12, 16, v12
	v_mul_f32_e32 v0, v13, v0
	v_mul_f32_e32 v6, v6, v12
	v_bfe_u32 v12, v0, 16, 1
	v_bfe_u32 v13, v6, 16, 1
	v_add3_u32 v0, v0, v12, s37
	v_add3_u32 v6, v6, v13, s37
	global_store_short_d16_hi v[4:5], v0, off offset:1792
	global_store_short_d16_hi v[4:5], v6, off offset:1856
	v_mov_b32_e32 v0, v92
	s_nop 0
	v_mov_b32_e32 v6, v93
	v_add_f32_e32 v12, v15, v7
	v_add_u32_e32 v4, 26, v50
	v_add_f32_e32 v7, v31, v7
	v_ashrrev_i32_e32 v5, 31, v4
	v_lshlrev_b64 v[10:11], 9, v[4:5]
	v_addc_co_u32_e32 v3, vcc, 0, v3, vcc
	v_lshl_add_u64 v[10:11], v[52:53], 0, v[10:11]
	v_lshlrev_b64 v[4:5], 11, v[4:5]
	v_lshl_add_u64 v[4:5], v[42:43], 0, v[4:5]
	v_add_co_u32_e32 v4, vcc, s35, v4
	v_lshlrev_b32_e32 v0, 16, v0
	v_lshlrev_b32_e32 v6, 16, v6
	v_mul_f32_e32 v0, v12, v0
	v_mul_f32_e32 v6, v7, v6
	v_bfe_u32 v7, v0, 16, 1
	v_bfe_u32 v12, v6, 16, 1
	v_add3_u32 v0, v0, v7, s37
	v_add3_u32 v6, v6, v12, s37
	global_store_short_d16_hi v[2:3], v0, off offset:1792
	global_store_short_d16_hi v[2:3], v6, off offset:1856
	v_mov_b32_e32 v0, v94
	s_nop 0
	v_mov_b32_e32 v10, v95
	v_add_f32_e32 v11, v16, v8
	v_add_u32_e32 v2, 27, v50
	v_add_f32_e32 v8, v32, v8
	v_ashrrev_i32_e32 v3, 31, v2
	v_lshlrev_b64 v[6:7], 9, v[2:3]
	v_addc_co_u32_e32 v5, vcc, 0, v5, vcc
	v_lshl_add_u64 v[6:7], v[52:53], 0, v[6:7]
	v_lshlrev_b64 v[2:3], 11, v[2:3]
	v_lshl_add_u64 v[2:3], v[42:43], 0, v[2:3]
	v_add_co_u32_e32 v2, vcc, s35, v2
	v_lshlrev_b32_e32 v0, 16, v0
	v_lshlrev_b32_e32 v10, 16, v10
	v_mul_f32_e32 v0, v11, v0
	v_mul_f32_e32 v8, v8, v10
	v_bfe_u32 v10, v0, 16, 1
	v_bfe_u32 v11, v8, 16, 1
	v_add3_u32 v0, v0, v10, s37
	v_add3_u32 v8, v8, v11, s37
	global_store_short_d16_hi v[4:5], v0, off offset:1792
	global_store_short_d16_hi v[4:5], v8, off offset:1856
	v_mov_b32_e32 v0, v96
	s_nop 0
	v_mov_b32_e32 v4, v97
	v_add_f32_e32 v5, v17, v9
	v_add_f32_e32 v6, v33, v9
	v_addc_co_u32_e32 v3, vcc, 0, v3, vcc
	v_lshlrev_b32_e32 v0, 16, v0
	v_lshlrev_b32_e32 v4, 16, v4
	v_mul_f32_e32 v0, v5, v0
	v_mul_f32_e32 v4, v6, v4
	v_bfe_u32 v5, v0, 16, 1
	v_bfe_u32 v6, v4, 16, 1
	v_add3_u32 v0, v0, v5, s37
	v_add3_u32 v4, v4, v6, s37
	global_store_short_d16_hi v[2:3], v0, off offset:1792
	global_store_short_d16_hi v[2:3], v4, off offset:1856
	s_barrier
